# attention non-diagonal tiles software-pipelined: QK(t) then PV(t-1) MFMAs interleaved with tile t exp/sum/cvt, both wave halves lag PV by one tile
# baseline (speedup 1.0000x reference)
; __device__ __forceinline__ unsigned pk2(float lo, float hi) { f32x2 v = {lo, hi}; bf16x2_t b = __builtin_convertvector(v, bf16x2_t); return __builtin_bit_cast(unsigned, b); }
; #define ATT_PV(slot) do { bf16x8 va[4], vb[4]; ATT_LDV(va, slot, 0); ATT_SB; ATT_LDV(vb, slot, 1); ATT_SB; ATT_MMV(va, 0); ATT_SB; ATT_LDV(va, slot, 2); ATT_SB; ATT_MMV(vb, 1); ATT_SB; \
;         ATT_LDV(vb, slot, 3); ATT_SB; ATT_MMV(va, 2); ATT_SB; ATT_MMV(vb, 3); ATT_SB; } while (0)
; template <bool NOSHIFT> __device__ __forceinline__ void diff_attn_unit(LAS unsigned char* lds, bf16_t* proj, const bf16_t* VT, int b, int h, int qb, const AttnConsts ac, const float* gsub, const int tid, bf16_t* obuf, int opitch, int ocol) {
;     ...
;             for (int kk = 0; kk < 4; ++kk) { const int mt = kk >> 1, r0 = 8 * (kk & 1); u32x4 w;
;                 w.x = pk2(p[mt][r0], p[mt][r0 + 1]); w.y = pk2(p[mt][r0 + 2], p[mt][r0 + 3]); w.z = pk2(p[mt][r0 + 4], p[mt][r0 + 5]); w.w = pk2(p[mt][r0 + 6], p[mt][r0 + 7]);
;                 pf[kk] = __builtin_bit_cast(bf16x8, w); }
;             if (c == 0) ATT_PV(sl_cur);
.LBB1_280:
	v_cvt_pk_bf16_f32 v104, v32, v33
	v_and_b32_e32 v32, 7, v65
	v_bitop3_b32 v33, v65, v64, 7 bitop3:0x6c
	v_lshlrev_b32_e32 v192, 4, v33
	v_bitop3_b32 v33, v64, v32, 2 bitop3:0x36
	v_lshlrev_b32_e32 v190, 7, v112
	s_add_i32 s14, 0, 0x10000
	v_lshlrev_b32_e32 v191, 4, v33
	v_bitop3_b32 v33, v64, v32, 4 bitop3:0x36
	v_bitop3_b32 v32, v64, v32, 6 bitop3:0x36
	v_add_u32_e32 v0, s14, v190
	v_lshlrev_b32_e32 v189, 4, v33
	v_lshlrev_b32_e32 v188, 4, v32
	s_cmpk_lt_u32 s77, 0x100
	v_cvt_pk_bf16_f32 v105, v34, v35
	v_cvt_pk_bf16_f32 v106, v36, v37
	v_cvt_pk_bf16_f32 v107, v38, v39
	v_cvt_pk_bf16_f32 v100, v40, v41
	v_cvt_pk_bf16_f32 v101, v42, v43
	v_cvt_pk_bf16_f32 v102, v44, v45
	v_cvt_pk_bf16_f32 v103, v46, v47
	v_cvt_pk_bf16_f32 v96, v48, v49
	v_add_u32_e32 v193, v0, v192
	v_add_u32_e32 v204, v0, v191
	v_add_u32_e32 v205, v0, v189
	v_add_u32_e32 v206, v0, v188
	s_cselect_b64 s[72:73], -1, 0
	s_cmpk_gt_u32 s77, 0xff
	v_cvt_pk_bf16_f32 v97, v2, v3
	v_cvt_pk_bf16_f32 v98, v4, v5
	v_cvt_pk_bf16_f32 v99, v6, v7
	v_cvt_pk_bf16_f32 v108, v8, v9
	v_cvt_pk_bf16_f32 v109, v10, v11
	v_cvt_pk_bf16_f32 v110, v12, v13
	v_cvt_pk_bf16_f32 v111, v14, v15
	s_cbranch_scc1 .LBB1_283
	s_cmp_lg_u32 s84, 0
	s_cbranch_scc1 .LBB1_283
	ds_read_b128 v[2:5], v193
	ds_read_b128 v[6:9], v193 offset:4096
	ds_read_b128 v[10:13], v193 offset:8192
	ds_read_b128 v[32:35], v193 offset:12288
	ds_read_b128 v[118:121], v204
	ds_read_b128 v[122:125], v204 offset:4096
	ds_read_b128 v[126:129], v204 offset:8192
	ds_read_b128 v[130:133], v204 offset:12288
	s_setprio 1
	s_waitcnt lgkmcnt(7)
	v_mfma_f32_32x32x16_bf16 v[80:95], v[2:5], v[104:107], 0
	s_waitcnt lgkmcnt(6)
	v_mfma_f32_32x32x16_bf16 v[64:79], v[6:9], v[104:107], 0
	s_waitcnt lgkmcnt(5)
	v_mfma_f32_32x32x16_bf16 v[48:63], v[10:13], v[104:107], 0
	s_waitcnt lgkmcnt(4)
	v_mfma_f32_32x32x16_bf16 v[32:47], v[32:35], v[104:107], 0
	s_setprio 0
	ds_read_b128 v[2:5], v205
	ds_read_b128 v[6:9], v205 offset:4096
	ds_read_b128 v[10:13], v205 offset:8192
	ds_read_b128 v[134:137], v205 offset:12288
	s_setprio 1
	s_waitcnt lgkmcnt(7)
	v_mfma_f32_32x32x16_bf16 v[80:95], v[118:121], v[100:103], v[80:95]
	s_waitcnt lgkmcnt(6)
	v_mfma_f32_32x32x16_bf16 v[64:79], v[122:125], v[100:103], v[64:79]
	s_waitcnt lgkmcnt(5)
	v_mfma_f32_32x32x16_bf16 v[48:63], v[126:129], v[100:103], v[48:63]
	s_waitcnt lgkmcnt(4)
	v_mfma_f32_32x32x16_bf16 v[32:47], v[130:133], v[100:103], v[32:47]
	s_setprio 0
	ds_read_b128 v[118:121], v206
	ds_read_b128 v[122:125], v206 offset:4096
	ds_read_b128 v[126:129], v206 offset:8192
	ds_read_b128 v[130:133], v206 offset:12288
	s_setprio 1
	s_waitcnt lgkmcnt(7)
	v_mfma_f32_32x32x16_bf16 v[80:95], v[2:5], v[96:99], v[80:95]
	s_waitcnt lgkmcnt(6)
	v_mfma_f32_32x32x16_bf16 v[64:79], v[6:9], v[96:99], v[64:79]
	s_waitcnt lgkmcnt(5)
	v_mfma_f32_32x32x16_bf16 v[48:63], v[10:13], v[96:99], v[48:63]
	s_waitcnt lgkmcnt(4)
	v_mfma_f32_32x32x16_bf16 v[32:47], v[134:137], v[96:99], v[32:47]
	s_setprio 0
	s_setprio 1
	s_waitcnt lgkmcnt(3)
	v_mfma_f32_32x32x16_bf16 v[80:95], v[118:121], v[108:111], v[80:95]
	s_waitcnt lgkmcnt(2)
	v_mfma_f32_32x32x16_bf16 v[64:79], v[122:125], v[108:111], v[64:79]
	s_waitcnt lgkmcnt(1)
	v_mfma_f32_32x32x16_bf16 v[48:63], v[126:129], v[108:111], v[48:63]
	s_waitcnt lgkmcnt(0)
	v_mfma_f32_32x32x16_bf16 v[32:47], v[130:133], v[108:111], v[32:47]
	s_setprio 0
	s_and_b64 vcc, exec, s[74:75]
	s_cbranch_vccnz .LBB1_284

; #define LAS __attribute__((address_space(3)))
; template <bool NOSHIFT> __device__ __forceinline__ void diff_attn_unit(LAS unsigned char* lds, bf16_t* proj, const bf16_t* VT, int b, int h, int qb, const AttnConsts ac, const float* gsub, const int tid, bf16_t* obuf, int opitch, int ocol) {
;     ...
;     for (int t = 0; t < NT; ++t) {
;         const int bo = (t & 3) * 16384, sl_cur = bo, sl_prev = ((t - 1) & 3) * 16384;
;         if (t + 2 < NT) ATT_ISSUE(t + 2);
;         const int kv0 = 64 * t;
;         if (c == 1 && t >= 1 && kv0 - 64 <= qmax) ATT_PV(sl_prev);
;         if (kv0 <= qmax) {
;             f32x16 p[2];
;             bf16x8 kf[2][4];
; #pragma unroll
;             for (int mt = 0; mt < 2; ++mt)
; #pragma unroll
;                 for (int ks = 0; ks < 4; ++ks) kf[mt][ks] = *(const LAS bf16x8*)(lds + bo + koff[mt][ks]);
;             if constexpr (!NOSHIFT) {
; #pragma unroll
;                 for (int mt = 0; mt < 2; ++mt)
; #pragma unroll
;                     for (int r = 0; r < 16; ++r) p[mt][r] = -ac.Mfix;
;             }
;             ATT_SB;
;             __builtin_amdgcn_s_setprio(1);
; #pragma unroll
;             for (int ks = 0; ks < 4; ++ks)
; #pragma unroll
;                 for (int mt = 0; mt < 2; ++mt) {
;                     if (NOSHIFT && ks == 0) { const f32x16 z = {0.f, 0.f, 0.f, 0.f, 0.f, 0.f, 0.f, 0.f, 0.f, 0.f, 0.f, 0.f, 0.f, 0.f, 0.f, 0.f}; p[mt] = __builtin_amdgcn_mfma_f32_32x32x16_bf16(kf[mt][ks], qf[ks], z, 0, 0, 0); }
;                     else p[mt] = __builtin_amdgcn_mfma_f32_32x32x16_bf16(kf[mt][ks], qf[ks], p[mt], 0, 0, 0);
;                 }
;             __builtin_amdgcn_s_setprio(0);
;             ATT_SB;
;             const bool diag = (t >= 2 * qb);
;             if (diag) {
;                 const int qrel = qrow - kv0 - 8 * hi;
; #pragma unroll
;                 for (int mt = 0; mt < 2; ++mt)
; #pragma unroll
;                     for (int r = 0; r < 16; ++r) { float v = __builtin_amdgcn_exp2f(p[mt][r]); if (32 * mt + 16 * (r >> 3) + (r & 7) > qrel) v = 0.f; p[mt][r] = v; l += v; }
;             } else {
; #pragma unroll
;                 for (int mt = 0; mt < 2; ++mt)
; #pragma unroll
;                     for (int r = 0; r < 16; ++r) { const float v = __builtin_amdgcn_exp2f(p[mt][r]); p[mt][r] = v; l += v; }
;             }
;             asm volatile("" ::: "memory");
; #pragma unroll
.LBB1_287:
	s_cmp_lg_u32 s82, 1
	s_cbranch_scc1 .Lfp_go
	v_mov_b64_e32 v[208:209], v[104:105]
	v_mov_b64_e32 v[210:211], v[106:107]
	v_mov_b64_e32 v[212:213], v[100:101]
	v_mov_b64_e32 v[214:215], v[102:103]
	v_mov_b64_e32 v[216:217], v[96:97]
	v_mov_b64_e32 v[218:219], v[98:99]
	v_mov_b64_e32 v[220:221], v[108:109]
	v_mov_b64_e32 v[222:223], v[110:111]
.Lfp_go:
	s_addk_i32 s14, 0x4000
	s_and_b32 s15, s14, 0xc000
	v_add_u32_e32 v7, s15, v179
	v_add_u32_e32 v96, s15, v183
	v_add_u32_e32 v97, s15, v186
	v_add_u32_e32 v98, s15, v187
	ds_read_b128 v[8:11], v7
	ds_read_b128 v[12:15], v7 offset:8192
	ds_read_b128 v[128:131], v96
	ds_read_b128 v[132:135], v96 offset:8192
	ds_read_b128 v[136:139], v97
	ds_read_b128 v[140:143], v97 offset:8192
	ds_read_b128 v[144:147], v98
	ds_read_b128 v[148:151], v98 offset:8192
	s_add_i32 s80, s14, 0x8000
	v_lshl_add_u64 v[152:153], s[96:97], 0, v[4:5]
	s_mov_b64 s[16:17], 0x9e82000
	s_and_b32 s80, s80, 0xc000
	v_lshl_add_u64 v[154:155], v[152:153], 0, s[16:17]
	s_add_i32 s81, s80, s59
	s_mov_b32 m0, s81
	v_lshl_add_u64 v[156:157], s[96:97], 0, v[2:3]
	global_load_lds_dwordx4 v[154:155], off
	s_mov_b64 s[16:17], 0x9f42000
	s_addk_i32 s81, 0x2000
	v_lshl_add_u64 v[152:153], v[152:153], 0, s[16:17]
	s_mov_b32 m0, s81
	s_mov_b64 s[16:17], 0x21a00180
	global_load_lds_dwordx4 v[152:153], off
	v_lshl_add_u64 v[158:159], v[156:157], 0, s[16:17]
	s_add_i32 s81, s80, s54
	s_mov_b32 m0, s81
	s_mov_b64 s[16:17], 0x21c00180
	global_load_lds_dwordx4 v[158:159], off
	v_lshl_add_u64 v[156:157], v[156:157], 0, s[16:17]
	s_addk_i32 s81, 0x2000
	s_mov_b32 m0, s81
	s_nop 0
	global_load_lds_dwordx4 v[156:157], off
	s_setprio 1
	s_waitcnt lgkmcnt(7)
	v_mfma_f32_32x32x16_bf16 v[96:111], v[8:11], v[160:163], 0
	s_waitcnt lgkmcnt(6)
	v_mfma_f32_32x32x16_bf16 v[112:127], v[12:15], v[160:163], 0
	s_waitcnt lgkmcnt(5)
	v_mfma_f32_32x32x16_bf16 v[96:111], v[128:131], v[164:167], v[96:111]
	s_waitcnt lgkmcnt(4)
	v_mfma_f32_32x32x16_bf16 v[112:127], v[132:135], v[164:167], v[112:127]
	s_waitcnt lgkmcnt(3)
	v_mfma_f32_32x32x16_bf16 v[96:111], v[136:139], v[168:171], v[96:111]
	s_waitcnt lgkmcnt(2)
	v_mfma_f32_32x32x16_bf16 v[112:127], v[140:143], v[168:171], v[112:127]
	s_waitcnt lgkmcnt(1)
	v_mfma_f32_32x32x16_bf16 v[96:111], v[144:147], v[172:175], v[96:111]
	s_waitcnt lgkmcnt(0)
	v_mfma_f32_32x32x16_bf16 v[112:127], v[148:151], v[172:175], v[112:127]
	s_add_i32 s80, s14, 0xc000
	s_and_b32 s80, s80, 0xc000
	v_add_u32_e32 v144, s80, v193
	ds_read_b128 v[128:131], v144
	ds_read_b128 v[132:135], v144 offset:4096
	ds_read_b128 v[136:139], v144 offset:8192
	ds_read_b128 v[140:143], v144 offset:12288
	v_add_u32_e32 v145, s80, v204
	ds_read_b128 v[224:227], v145
	ds_read_b128 v[228:231], v145 offset:4096
	ds_read_b128 v[232:235], v145 offset:8192
	ds_read_b128 v[236:239], v145 offset:12288
	s_nop 1
	v_exp_f32_e32 v96, v96
	v_exp_f32_e32 v97, v97
	v_exp_f32_e32 v98, v98
	v_exp_f32_e32 v99, v99
	v_exp_f32_e32 v100, v100
	v_exp_f32_e32 v101, v101
	v_exp_f32_e32 v102, v102
	v_exp_f32_e32 v103, v103
	s_waitcnt lgkmcnt(7)
	v_mfma_f32_32x32x16_bf16 v[80:95], v[128:131], v[208:211], v[80:95]
	v_exp_f32_e32 v104, v104
	v_exp_f32_e32 v105, v105
	v_add_f32_e32 v7, v207, v96
	v_add_f32_e32 v7, v97, v7
	s_waitcnt lgkmcnt(6)
	v_mfma_f32_32x32x16_bf16 v[64:79], v[132:135], v[208:211], v[64:79]
	v_exp_f32_e32 v106, v106
	v_exp_f32_e32 v107, v107
	v_add_f32_e32 v7, v98, v7
	v_add_f32_e32 v7, v99, v7
	s_waitcnt lgkmcnt(5)
	v_mfma_f32_32x32x16_bf16 v[48:63], v[136:139], v[208:211], v[48:63]
	v_exp_f32_e32 v108, v108
	v_exp_f32_e32 v109, v109
	v_add_f32_e32 v7, v100, v7
	v_add_f32_e32 v7, v101, v7
	s_waitcnt lgkmcnt(4)
	v_mfma_f32_32x32x16_bf16 v[32:47], v[140:143], v[208:211], v[32:47]
	v_exp_f32_e32 v110, v110
	v_exp_f32_e32 v111, v111
	v_add_f32_e32 v7, v102, v7
	v_add_f32_e32 v7, v103, v7
	v_add_u32_e32 v144, s80, v205
	ds_read_b128 v[128:131], v144
	ds_read_b128 v[132:135], v144 offset:4096
	ds_read_b128 v[136:139], v144 offset:8192
	ds_read_b128 v[140:143], v144 offset:12288
	s_waitcnt lgkmcnt(7)
	v_mfma_f32_32x32x16_bf16 v[80:95], v[224:227], v[212:215], v[80:95]
	v_cvt_pk_bf16_f32 v208, v96, v97
	v_cvt_pk_bf16_f32 v209, v98, v99
	v_exp_f32_e32 v112, v112
	v_exp_f32_e32 v113, v113
	v_add_f32_e32 v7, v104, v7
	s_waitcnt lgkmcnt(6)
	v_mfma_f32_32x32x16_bf16 v[64:79], v[228:231], v[212:215], v[64:79]
	v_cvt_pk_bf16_f32 v210, v100, v101
	v_cvt_pk_bf16_f32 v211, v102, v103
	v_exp_f32_e32 v114, v114
	v_exp_f32_e32 v115, v115
	v_add_f32_e32 v7, v105, v7
	s_waitcnt lgkmcnt(5)
	v_mfma_f32_32x32x16_bf16 v[48:63], v[232:235], v[212:215], v[48:63]
	v_exp_f32_e32 v116, v116
	v_exp_f32_e32 v117, v117
	v_add_f32_e32 v7, v106, v7
	v_add_f32_e32 v7, v107, v7
	v_add_f32_e32 v7, v108, v7
	s_waitcnt lgkmcnt(4)
	v_mfma_f32_32x32x16_bf16 v[32:47], v[236:239], v[212:215], v[32:47]
	v_exp_f32_e32 v118, v118
	v_exp_f32_e32 v119, v119
	v_add_f32_e32 v7, v109, v7
	v_add_f32_e32 v7, v110, v7
	v_add_f32_e32 v7, v111, v7
	v_add_u32_e32 v145, s80, v206
	ds_read_b128 v[224:227], v145
	ds_read_b128 v[228:231], v145 offset:4096
	ds_read_b128 v[232:235], v145 offset:8192
	ds_read_b128 v[236:239], v145 offset:12288
	s_waitcnt lgkmcnt(7)
	v_mfma_f32_32x32x16_bf16 v[80:95], v[128:131], v[216:219], v[80:95]
	v_cvt_pk_bf16_f32 v212, v104, v105
	v_cvt_pk_bf16_f32 v213, v106, v107
	v_exp_f32_e32 v120, v120
	v_exp_f32_e32 v121, v121
	v_add_f32_e32 v7, v112, v7
	s_waitcnt lgkmcnt(6)
	v_mfma_f32_32x32x16_bf16 v[64:79], v[132:135], v[216:219], v[64:79]
	v_cvt_pk_bf16_f32 v214, v108, v109
	v_cvt_pk_bf16_f32 v215, v110, v111
	v_exp_f32_e32 v122, v122
	v_exp_f32_e32 v123, v123
	v_add_f32_e32 v7, v113, v7
	s_waitcnt lgkmcnt(5)
	v_mfma_f32_32x32x16_bf16 v[48:63], v[136:139], v[216:219], v[48:63]
	v_exp_f32_e32 v124, v124
	v_exp_f32_e32 v125, v125
	v_add_f32_e32 v7, v114, v7
	v_add_f32_e32 v7, v115, v7
	v_add_f32_e32 v7, v116, v7
	s_waitcnt lgkmcnt(4)
	v_mfma_f32_32x32x16_bf16 v[32:47], v[140:143], v[216:219], v[32:47]
	v_exp_f32_e32 v126, v126
	v_exp_f32_e32 v127, v127
	v_add_f32_e32 v7, v117, v7
	v_add_f32_e32 v7, v118, v7
	v_add_f32_e32 v7, v119, v7
	s_waitcnt lgkmcnt(3)
	v_mfma_f32_32x32x16_bf16 v[80:95], v[224:227], v[220:223], v[80:95]
	v_cvt_pk_bf16_f32 v216, v112, v113
	v_cvt_pk_bf16_f32 v217, v114, v115
	v_cvt_pk_bf16_f32 v218, v116, v117
	v_cvt_pk_bf16_f32 v219, v118, v119
	s_waitcnt lgkmcnt(2)
	v_mfma_f32_32x32x16_bf16 v[64:79], v[228:231], v[220:223], v[64:79]
	v_add_f32_e32 v7, v120, v7
	v_add_f32_e32 v7, v121, v7
	v_add_f32_e32 v7, v122, v7
	v_add_f32_e32 v7, v123, v7
	s_waitcnt lgkmcnt(1)
	v_mfma_f32_32x32x16_bf16 v[48:63], v[232:235], v[220:223], v[48:63]
	v_add_f32_e32 v7, v124, v7
	v_add_f32_e32 v7, v125, v7
	v_add_f32_e32 v7, v126, v7
	v_add_f32_e32 v7, v127, v7
	s_waitcnt lgkmcnt(0)
	v_mfma_f32_32x32x16_bf16 v[32:47], v[236:239], v[220:223], v[32:47]
	v_cvt_pk_bf16_f32 v220, v120, v121
	v_cvt_pk_bf16_f32 v221, v122, v123
	v_cvt_pk_bf16_f32 v222, v124, v125
	v_cvt_pk_bf16_f32 v223, v126, v127
	s_setprio 0
	s_branch .LBB1_298
; #define ATT_PV(slot) do { bf16x8 va[4], vb[4]; ATT_LDV(va, slot, 0); ATT_SB; ATT_LDV(vb, slot, 1); ATT_SB; ATT_MMV(va, 0); ATT_SB; ATT_LDV(va, slot, 2); ATT_SB; ATT_MMV(vb, 1); ATT_SB; \
;         ATT_LDV(vb, slot, 3); ATT_SB; ATT_MMV(va, 2); ATT_SB; ATT_MMV(vb, 3); ATT_SB; } while (0)
; template <bool NOSHIFT> __device__ __forceinline__ void diff_attn_unit(LAS unsigned char* lds, bf16_t* proj, const bf16_t* VT, int b, int h, int qb, const AttnConsts ac, const float* gsub, const int tid, bf16_t* obuf, int opitch, int ocol) {
;     ...
;     for (int t = 0; t < NT; ++t) {
;         const int bo = (t & 3) * 16384, sl_cur = bo, sl_prev = ((t - 1) & 3) * 16384;
;         if (t + 2 < NT) ATT_ISSUE(t + 2);
;         const int kv0 = 64 * t;
;         if (c == 1 && t >= 1 && kv0 - 64 <= qmax) ATT_PV(sl_prev);
.LBB1_288:
	s_cmp_lg_u32 s82, s45
	s_cbranch_scc1 .Lsp_normal
	s_cmp_eq_u32 s45, 0
	s_cbranch_scc1 .Lsp_normal
	v_mov_b64_e32 v[104:105], v[208:209]
	v_mov_b64_e32 v[106:107], v[210:211]
	v_mov_b64_e32 v[100:101], v[212:213]
	v_mov_b64_e32 v[102:103], v[214:215]
	v_mov_b64_e32 v[96:97], v[216:217]
	v_mov_b64_e32 v[98:99], v[218:219]
	v_mov_b64_e32 v[108:109], v[220:221]
	v_mov_b64_e32 v[110:111], v[222:223]
	s_branch .Lsp_pvprev

; #define ATT_WAITBAR(N) asm volatile("s_waitcnt vmcnt(" #N ") lgkmcnt(0)\n\ts_barrier" ::: "memory")
; #define ATT_PV(slot) do { bf16x8 va[4], vb[4]; ATT_LDV(va, slot, 0); ATT_SB; ATT_LDV(vb, slot, 1); ATT_SB; ATT_MMV(va, 0); ATT_SB; ATT_LDV(va, slot, 2); ATT_SB; ATT_MMV(vb, 1); ATT_SB; \
;         ATT_LDV(vb, slot, 3); ATT_SB; ATT_MMV(va, 2); ATT_SB; ATT_MMV(vb, 3); ATT_SB; } while (0)
; template <bool NOSHIFT> __device__ __forceinline__ void diff_attn_unit(LAS unsigned char* lds, bf16_t* proj, const bf16_t* VT, int b, int h, int qb, const AttnConsts ac, const float* gsub, const int tid, bf16_t* obuf, int opitch, int ocol) {
;     ...
;     ATT_ISSUE(0); ATT_ISSUE(1);
;     ATT_WAITBAR(4);
;     for (int t = 0; t < NT; ++t) {
;         const int bo = (t & 3) * 16384, sl_cur = bo, sl_prev = ((t - 1) & 3) * 16384;
;         if (t + 2 < NT) ATT_ISSUE(t + 2);
;         const int kv0 = 64 * t;
;         if (c == 1 && t >= 1 && kv0 - 64 <= qmax) ATT_PV(sl_prev);
.Lsp_pvprev:
	s_add_i32 s15, s14, 0x10000
	s_and_b32 s15, s15, 0xc000
	v_add_u32_e32 v7, s15, v193
	ds_read_b128 v[8:11], v7
	ds_read_b128 v[12:15], v7 offset:4096
	ds_read_b128 v[112:115], v7 offset:8192
	ds_read_b128 v[116:119], v7 offset:12288
	v_add_u32_e32 v7, s15, v204
	ds_read_b128 v[120:123], v7
	ds_read_b128 v[124:127], v7 offset:4096
	ds_read_b128 v[128:131], v7 offset:8192
	ds_read_b128 v[132:135], v7 offset:12288
	s_setprio 1
	s_waitcnt lgkmcnt(7)
	v_mfma_f32_32x32x16_bf16 v[80:95], v[8:11], v[104:107], v[80:95]
	s_waitcnt lgkmcnt(6)
	v_mfma_f32_32x32x16_bf16 v[64:79], v[12:15], v[104:107], v[64:79]
	s_waitcnt lgkmcnt(5)
	v_mfma_f32_32x32x16_bf16 v[48:63], v[112:115], v[104:107], v[48:63]
	s_waitcnt lgkmcnt(4)
	v_mfma_f32_32x32x16_bf16 v[32:47], v[116:119], v[104:107], v[32:47]
	s_setprio 0
	v_add_u32_e32 v7, s15, v205
	ds_read_b128 v[8:11], v7
	ds_read_b128 v[12:15], v7 offset:4096
	ds_read_b128 v[112:115], v7 offset:8192
	ds_read_b128 v[116:119], v7 offset:12288
	s_setprio 1
	s_waitcnt lgkmcnt(7)
	v_mfma_f32_32x32x16_bf16 v[80:95], v[120:123], v[100:103], v[80:95]
	s_waitcnt lgkmcnt(6)
	v_mfma_f32_32x32x16_bf16 v[64:79], v[124:127], v[100:103], v[64:79]
	s_waitcnt lgkmcnt(5)
	v_mfma_f32_32x32x16_bf16 v[48:63], v[128:131], v[100:103], v[48:63]
	s_waitcnt lgkmcnt(4)
	v_mfma_f32_32x32x16_bf16 v[32:47], v[132:135], v[100:103], v[32:47]
	s_setprio 0
	v_add_u32_e32 v7, s15, v206
	ds_read_b128 v[120:123], v7
	ds_read_b128 v[124:127], v7 offset:4096
	ds_read_b128 v[128:131], v7 offset:8192
	ds_read_b128 v[132:135], v7 offset:12288
	s_setprio 1
	s_waitcnt lgkmcnt(7)
	v_mfma_f32_32x32x16_bf16 v[80:95], v[8:11], v[96:99], v[80:95]
	s_waitcnt lgkmcnt(6)
	v_mfma_f32_32x32x16_bf16 v[64:79], v[12:15], v[96:99], v[64:79]
	s_waitcnt lgkmcnt(5)
	v_mfma_f32_32x32x16_bf16 v[48:63], v[112:115], v[96:99], v[48:63]
	s_waitcnt lgkmcnt(4)
	v_mfma_f32_32x32x16_bf16 v[32:47], v[116:119], v[96:99], v[32:47]
	s_setprio 0
	s_setprio 1
	s_waitcnt lgkmcnt(3)
	v_mfma_f32_32x32x16_bf16 v[80:95], v[120:123], v[108:111], v[80:95]
	s_waitcnt lgkmcnt(2)
	v_mfma_f32_32x32x16_bf16 v[64:79], v[124:127], v[108:111], v[64:79]
	s_waitcnt lgkmcnt(1)
	v_mfma_f32_32x32x16_bf16 v[48:63], v[128:131], v[108:111], v[48:63]
	s_waitcnt lgkmcnt(0)
	v_mfma_f32_32x32x16_bf16 v[32:47], v[132:135], v[108:111], v[32:47]
	s_setprio 0
